# nt hint on all GEMM epilogue stores on top of v33
# baseline (speedup 1.0000x reference)
.LBB0_118:
	s_cmp_lt_i32 s18, 2
	s_cselect_b64 vcc, -1, 0
	v_cndmask_b32_e32 v172, 1.0, v193, vcc
	v_pk_mul_f32 v[126:127], v[172:173], v[126:127] op_sel_hi:[0,1]
	v_pk_mul_f32 v[124:125], v[172:173], v[124:125] op_sel_hi:[0,1]
	v_pk_mul_f32 v[208:209], v[172:173], v[122:123] op_sel_hi:[0,1]
	v_pk_mul_f32 v[122:123], v[172:173], v[120:121] op_sel_hi:[0,1]
	v_cvt_pk_bf16_f32 v120, v124, v125
	v_cvt_pk_bf16_f32 v121, v126, v127
	v_cvt_pk_bf16_f32 v122, v122, v123
	v_cvt_pk_bf16_f32 v123, v208, v209
	s_and_b64 vcc, exec, s[6:7]
	global_store_dwordx4 v[178:179], v[120:123], off nt
	s_cbranch_vccnz .LBB0_122
	s_nop 0
	v_and_b32_e32 v121, 64, v192
	v_xor_b32_e32 v120, 16, v192
	v_add_u32_e32 v121, 64, v121
	v_cmp_lt_i32_e32 vcc, v120, v121
	s_nop 1
	v_cndmask_b32_e32 v120, v192, v120, vcc
	v_lshlrev_b32_e32 v125, 2, v120
	ds_bpermute_b32 v122, v125, v116
	ds_bpermute_b32 v120, v125, v112
	ds_bpermute_b32 v123, v125, v117
	ds_bpermute_b32 v121, v125, v113
	ds_bpermute_b32 v126, v125, v118
	ds_bpermute_b32 v124, v125, v114
	ds_bpermute_b32 v127, v125, v119
	ds_bpermute_b32 v125, v125, v115
	s_and_saveexec_b64 s[8:9], s[14:15]
	s_cbranch_execz .LBB0_121
	s_waitcnt lgkmcnt(0)
	v_mul_f32_e32 v127, v164, v127
	s_waitcnt vmcnt(0)
	v_mov_b32_e32 v178, v136
	v_mov_b32_e32 v179, v138
	v_mov_b32_e32 v138, v137
	v_mov_b32_e32 v136, v119
	v_mov_b32_e32 v137, v143
	v_mov_b32_e32 v143, v127
	v_mul_f32_e32 v126, v164, v126
	v_pk_mul_f32 v[136:137], v[136:137], v[142:143]
	v_pk_mul_f32 v[122:123], v[164:165], v[122:123]
	v_mul_f32_e32 v118, v118, v140
	v_mul_f32_e32 v126, v141, v126
	v_mov_b32_e32 v119, v136
	v_mov_b32_e32 v127, v137
	v_mul_f32_e32 v125, v164, v125
	v_pk_mul_f32 v[122:123], v[138:139], v[122:123]
	v_pk_add_f32 v[118:119], v[118:119], v[126:127]
	v_mov_b32_e32 v126, v115
	v_mov_b32_e32 v127, v131
	v_mov_b32_e32 v131, v125
	v_pk_fma_f32 v[116:117], v[116:117], v[178:179], v[122:123]
	v_mov_b32_e32 v123, v134
	v_pk_mul_f32 v[120:121], v[164:165], v[120:121]
	v_mov_b32_e32 v134, v133
	v_mul_f32_e32 v124, v164, v124
	v_pk_mul_f32 v[126:127], v[126:127], v[130:131]
	v_mov_b32_e32 v122, v132
	v_pk_mul_f32 v[120:121], v[134:135], v[120:121]
	v_mul_f32_e32 v114, v114, v128
	v_mul_f32_e32 v124, v129, v124
	v_mov_b32_e32 v115, v126
	v_mov_b32_e32 v125, v127
	v_pk_fma_f32 v[112:113], v[112:113], v[122:123], v[120:121]
	v_pk_add_f32 v[114:115], v[114:115], v[124:125]

.LBB0_126:
	v_mov_b32_e32 v173, v172
	v_mov_b32_e32 v122, v172
	v_mov_b32_e32 v123, v172
	v_pk_mul_f32 v[118:119], v[122:123], v[118:119]
	v_pk_mul_f32 v[116:117], v[172:173], v[116:117]
	v_pk_mul_f32 v[122:123], v[122:123], v[114:115]
	v_pk_mul_f32 v[114:115], v[172:173], v[112:113]
	s_waitcnt vmcnt(0)
	v_or_b32_e32 v134, 16, v206
	v_cvt_pk_bf16_f32 v112, v116, v117
	v_cvt_pk_bf16_f32 v113, v118, v119
	v_cvt_pk_bf16_f32 v114, v114, v115
	v_cvt_pk_bf16_f32 v115, v122, v123
	s_and_b64 vcc, exec, s[6:7]
	v_cmp_gt_i32_e64 s[10:11], s53, v134
	global_store_dwordx4 v[120:121], v[112:115], off nt
	s_cbranch_vccnz .LBB0_128
	s_nop 0
	v_cndmask_b32_e64 v112, v194, v195, s[10:11]
	v_and_b32_e32 v112, v112, v134
	v_lshlrev_b32_e32 v112, 6, v112
	global_load_dwordx4 v[120:123], v112, s[16:17]
	global_load_dwordx4 v[124:127], v112, s[16:17] offset:16
	global_load_dwordx4 v[116:119], v112, s[16:17] offset:32
	s_nop 0
	global_load_dwordx4 v[112:115], v112, s[16:17] offset:48
	s_branch .LBB0_129

.LBB0_139:
	v_mov_b32_e32 v134, v172
	s_waitcnt lgkmcnt(2)
	v_mov_b32_e32 v135, v172
	v_pk_mul_f32 v[110:111], v[134:135], v[110:111]
	v_pk_mul_f32 v[108:109], v[172:173], v[108:109]
	v_pk_mul_f32 v[134:135], v[134:135], v[106:107]
	v_pk_mul_f32 v[106:107], v[172:173], v[104:105]
	v_cvt_pk_bf16_f32 v104, v108, v109
	v_cvt_pk_bf16_f32 v105, v110, v111
	v_cvt_pk_bf16_f32 v106, v106, v107
	v_cvt_pk_bf16_f32 v107, v134, v135
	s_and_b64 vcc, exec, s[6:7]
	global_store_dwordx4 v[132:133], v[104:107], off nt
	s_cbranch_vccz .LBB0_145
	s_and_b64 vcc, exec, s[8:9]
	s_mov_b64 s[12:13], -1
	s_cbranch_vccz .LBB0_148

.LBB0_143:
	s_waitcnt lgkmcnt(7)
	v_mov_b32_e32 v106, v172
	s_waitcnt lgkmcnt(5)
	v_mov_b32_e32 v107, v172
	v_pk_mul_f32 v[102:103], v[106:107], v[102:103]
	v_pk_mul_f32 v[100:101], v[172:173], v[100:101]
	v_pk_mul_f32 v[106:107], v[106:107], v[98:99]
	v_pk_mul_f32 v[98:99], v[172:173], v[96:97]
	s_waitcnt vmcnt(2)
	v_or_b32_e32 v118, 32, v206
	v_cvt_pk_bf16_f32 v96, v100, v101
	v_cvt_pk_bf16_f32 v97, v102, v103
	v_cvt_pk_bf16_f32 v98, v98, v99
	v_cvt_pk_bf16_f32 v99, v106, v107
	s_and_b64 vcc, exec, s[6:7]
	v_cmp_gt_i32_e64 s[12:13], s53, v118
	s_waitcnt lgkmcnt(4)
	global_store_dwordx4 v[104:105], v[96:99], off nt
	s_cbranch_vccnz .LBB0_149
	s_nop 0
	v_cndmask_b32_e64 v96, v198, v199, s[12:13]
	v_and_b32_e32 v96, v96, v118
	v_lshlrev_b32_e32 v96, 6, v96
	global_load_dwordx4 v[104:107], v96, s[16:17]
	s_waitcnt lgkmcnt(0)
	global_load_dwordx4 v[108:111], v96, s[16:17] offset:16
	global_load_dwordx4 v[100:103], v96, s[16:17] offset:32
	s_nop 0
	global_load_dwordx4 v[96:99], v96, s[16:17] offset:48
	s_and_b64 vcc, exec, s[10:11]
	s_waitcnt vmcnt(6)
	v_mov_b64_e32 v[112:113], 0
	s_cbranch_vccz .LBB0_150
	s_branch .LBB0_151

.LBB0_159:
	v_mov_b32_e32 v118, v172
	s_waitcnt lgkmcnt(2)
	v_mov_b32_e32 v119, v172
	v_pk_mul_f32 v[94:95], v[118:119], v[94:95]
	v_pk_mul_f32 v[92:93], v[172:173], v[92:93]
	v_pk_mul_f32 v[118:119], v[118:119], v[90:91]
	v_pk_mul_f32 v[90:91], v[172:173], v[88:89]
	v_cvt_pk_bf16_f32 v88, v92, v93
	v_cvt_pk_bf16_f32 v89, v94, v95
	v_cvt_pk_bf16_f32 v90, v90, v91
	v_cvt_pk_bf16_f32 v91, v118, v119
	s_and_b64 vcc, exec, s[6:7]
	global_store_dwordx4 v[116:117], v[88:91], off nt
	s_cbranch_vccz .LBB0_165
	s_and_b64 vcc, exec, s[8:9]
	s_mov_b64 s[12:13], -1
	s_cbranch_vccz .LBB0_168

.LBB0_163:
	s_waitcnt lgkmcnt(7)
	v_mov_b32_e32 v90, v172
	s_waitcnt lgkmcnt(5)
	v_mov_b32_e32 v91, v172
	v_pk_mul_f32 v[86:87], v[90:91], v[86:87]
	v_pk_mul_f32 v[84:85], v[172:173], v[84:85]
	v_pk_mul_f32 v[90:91], v[90:91], v[82:83]
	v_pk_mul_f32 v[82:83], v[172:173], v[80:81]
	s_waitcnt vmcnt(2)
	v_or_b32_e32 v102, 48, v206
	v_cvt_pk_bf16_f32 v80, v84, v85
	v_cvt_pk_bf16_f32 v81, v86, v87
	v_cvt_pk_bf16_f32 v82, v82, v83
	v_cvt_pk_bf16_f32 v83, v90, v91
	s_and_b64 vcc, exec, s[6:7]
	v_cmp_gt_i32_e64 s[12:13], s53, v102
	s_waitcnt lgkmcnt(4)
	global_store_dwordx4 v[88:89], v[80:83], off nt
	s_cbranch_vccnz .LBB0_169
	s_nop 0
	v_cndmask_b32_e64 v80, v202, v203, s[12:13]
	v_and_b32_e32 v80, v80, v102
	v_lshlrev_b32_e32 v80, 6, v80
	global_load_dwordx4 v[88:91], v80, s[16:17]
	s_waitcnt lgkmcnt(0)
	global_load_dwordx4 v[92:95], v80, s[16:17] offset:16
	global_load_dwordx4 v[84:87], v80, s[16:17] offset:32
	s_nop 0
	global_load_dwordx4 v[80:83], v80, s[16:17] offset:48
	s_and_b64 vcc, exec, s[10:11]
	s_waitcnt vmcnt(6)
	v_mov_b64_e32 v[96:97], 0
	s_cbranch_vccz .LBB0_170
	s_branch .LBB0_171

.LBB0_179:
	v_mov_b32_e32 v102, v172
	s_waitcnt lgkmcnt(2)
	v_mov_b32_e32 v103, v172
	v_pk_mul_f32 v[78:79], v[102:103], v[78:79]
	v_pk_mul_f32 v[76:77], v[172:173], v[76:77]
	v_pk_mul_f32 v[102:103], v[102:103], v[74:75]
	v_pk_mul_f32 v[74:75], v[172:173], v[72:73]
	v_cvt_pk_bf16_f32 v72, v76, v77
	v_cvt_pk_bf16_f32 v73, v78, v79
	v_cvt_pk_bf16_f32 v74, v74, v75
	v_cvt_pk_bf16_f32 v75, v102, v103
	s_and_b64 vcc, exec, s[6:7]
	global_store_dwordx4 v[100:101], v[72:75], off nt
	s_cbranch_vccz .LBB0_185
	s_and_b64 vcc, exec, s[8:9]
	s_mov_b64 s[12:13], -1
	s_cbranch_vccz .LBB0_188

.LBB0_183:
	s_waitcnt lgkmcnt(7)
	v_mov_b32_e32 v74, v172
	s_waitcnt lgkmcnt(5)
	v_mov_b32_e32 v75, v172
	v_pk_mul_f32 v[70:71], v[74:75], v[70:71]
	v_pk_mul_f32 v[68:69], v[172:173], v[68:69]
	v_pk_mul_f32 v[74:75], v[74:75], v[66:67]
	v_pk_mul_f32 v[66:67], v[172:173], v[64:65]
	v_cvt_pk_bf16_f32 v64, v68, v69
	v_cvt_pk_bf16_f32 v65, v70, v71
	v_cvt_pk_bf16_f32 v66, v66, v67
	v_cvt_pk_bf16_f32 v67, v74, v75
	s_waitcnt vmcnt(2)
	v_add_u32_e32 v86, 0x80, v206
	s_and_b64 vcc, exec, s[6:7]
	v_cmp_gt_i32_e64 s[12:13], s60, v206
	s_waitcnt lgkmcnt(4)
	global_store_dwordx4 v[72:73], v[64:67], off nt
	s_cbranch_vccnz .LBB0_189
	s_nop 0
	v_cndmask_b32_e64 v64, v184, v185, s[12:13]
	v_and_b32_e32 v64, v64, v86
	v_lshlrev_b32_e32 v64, 6, v64
	global_load_dwordx4 v[72:75], v64, s[16:17]
	s_waitcnt lgkmcnt(0)
	global_load_dwordx4 v[76:79], v64, s[16:17] offset:16
	global_load_dwordx4 v[68:71], v64, s[16:17] offset:32
	s_nop 0
	global_load_dwordx4 v[64:67], v64, s[16:17] offset:48
	s_and_b64 vcc, exec, s[10:11]
	s_waitcnt vmcnt(6)
	v_mov_b64_e32 v[80:81], 0
	s_cbranch_vccz .LBB0_190
	s_branch .LBB0_191

.LBB0_199:
	s_waitcnt lgkmcnt(0)
	v_mov_b32_e32 v88, v172
	v_mov_b32_e32 v89, v172
	v_pk_mul_f32 v[62:63], v[88:89], v[62:63]
	v_pk_mul_f32 v[60:61], v[172:173], v[60:61]
	v_pk_mul_f32 v[88:89], v[88:89], v[58:59]
	v_pk_mul_f32 v[58:59], v[172:173], v[56:57]
	v_cvt_pk_bf16_f32 v56, v60, v61
	v_cvt_pk_bf16_f32 v57, v62, v63
	v_cvt_pk_bf16_f32 v58, v58, v59
	v_cvt_pk_bf16_f32 v59, v88, v89
	s_and_b64 vcc, exec, s[6:7]
	global_store_dwordx4 v[84:85], v[56:59], off nt
	s_cbranch_vccz .LBB0_205
	s_and_b64 vcc, exec, s[8:9]
	s_mov_b64 s[12:13], -1
	s_cbranch_vccz .LBB0_208

.LBB0_203:
	s_waitcnt lgkmcnt(7)
	v_mov_b32_e32 v58, v172
	s_waitcnt lgkmcnt(5)
	v_mov_b32_e32 v59, v172
	v_pk_mul_f32 v[54:55], v[58:59], v[54:55]
	v_pk_mul_f32 v[52:53], v[172:173], v[52:53]
	v_pk_mul_f32 v[58:59], v[58:59], v[50:51]
	v_pk_mul_f32 v[50:51], v[172:173], v[48:49]
	v_cvt_pk_bf16_f32 v48, v52, v53
	v_cvt_pk_bf16_f32 v49, v54, v55
	v_cvt_pk_bf16_f32 v50, v50, v51
	v_cvt_pk_bf16_f32 v51, v58, v59
	s_waitcnt vmcnt(2)
	v_add_u32_e32 v70, 0x90, v206
	s_and_b64 vcc, exec, s[6:7]
	v_cmp_gt_i32_e64 s[12:13], s61, v206
	s_waitcnt lgkmcnt(4)
	global_store_dwordx4 v[56:57], v[48:51], off nt
	s_cbranch_vccnz .LBB0_209
	s_nop 0
	v_cndmask_b32_e64 v48, v194, v195, s[12:13]
	v_and_b32_e32 v48, v48, v70
	v_lshlrev_b32_e32 v48, 6, v48
	global_load_dwordx4 v[56:59], v48, s[16:17]
	s_waitcnt lgkmcnt(0)
	global_load_dwordx4 v[60:63], v48, s[16:17] offset:16
	global_load_dwordx4 v[52:55], v48, s[16:17] offset:32
	s_nop 0
	global_load_dwordx4 v[48:51], v48, s[16:17] offset:48
	s_and_b64 vcc, exec, s[10:11]
	s_waitcnt vmcnt(6)
	v_mov_b64_e32 v[64:65], 0
	s_cbranch_vccz .LBB0_210
	s_branch .LBB0_211

.LBB0_219:
	v_mov_b32_e32 v70, v172
	s_waitcnt lgkmcnt(2)
	v_mov_b32_e32 v71, v172
	v_pk_mul_f32 v[46:47], v[70:71], v[46:47]
	v_pk_mul_f32 v[44:45], v[172:173], v[44:45]
	v_pk_mul_f32 v[70:71], v[70:71], v[42:43]
	v_pk_mul_f32 v[42:43], v[172:173], v[40:41]
	v_cvt_pk_bf16_f32 v40, v44, v45
	v_cvt_pk_bf16_f32 v41, v46, v47
	v_cvt_pk_bf16_f32 v42, v42, v43
	v_cvt_pk_bf16_f32 v43, v70, v71
	s_and_b64 vcc, exec, s[6:7]
	global_store_dwordx4 v[68:69], v[40:43], off nt
	s_cbranch_vccz .LBB0_225
	s_and_b64 vcc, exec, s[8:9]
	s_mov_b64 s[12:13], -1
	s_cbranch_vccz .LBB0_228

.LBB0_223:
	s_waitcnt lgkmcnt(7)
	v_mov_b32_e32 v42, v172
	s_waitcnt lgkmcnt(5)
	v_mov_b32_e32 v43, v172
	v_pk_mul_f32 v[38:39], v[42:43], v[38:39]
	v_pk_mul_f32 v[36:37], v[172:173], v[36:37]
	v_pk_mul_f32 v[42:43], v[42:43], v[34:35]
	v_pk_mul_f32 v[34:35], v[172:173], v[32:33]
	v_cvt_pk_bf16_f32 v32, v36, v37
	v_cvt_pk_bf16_f32 v33, v38, v39
	v_cvt_pk_bf16_f32 v34, v34, v35
	v_cvt_pk_bf16_f32 v35, v42, v43
	s_waitcnt vmcnt(2)
	v_add_u32_e32 v54, 0xa0, v206
	s_and_b64 vcc, exec, s[6:7]
	v_cmp_gt_i32_e64 s[12:13], s62, v206
	s_waitcnt lgkmcnt(4)
	global_store_dwordx4 v[40:41], v[32:35], off nt
	s_cbranch_vccnz .LBB0_229
	s_nop 0
	v_cndmask_b32_e64 v32, v198, v199, s[12:13]
	v_and_b32_e32 v32, v32, v54
	v_lshlrev_b32_e32 v32, 6, v32
	global_load_dwordx4 v[40:43], v32, s[16:17]
	s_waitcnt lgkmcnt(0)
	global_load_dwordx4 v[44:47], v32, s[16:17] offset:16
	global_load_dwordx4 v[36:39], v32, s[16:17] offset:32
	s_nop 0
	global_load_dwordx4 v[32:35], v32, s[16:17] offset:48
	s_and_b64 vcc, exec, s[10:11]
	s_waitcnt vmcnt(6)
	v_mov_b64_e32 v[48:49], 0
	s_cbranch_vccz .LBB0_230
	s_branch .LBB0_231

.LBB0_239:
	v_mov_b32_e32 v54, v172
	s_waitcnt lgkmcnt(2)
	v_mov_b32_e32 v55, v172
	v_pk_mul_f32 v[30:31], v[54:55], v[30:31]
	v_pk_mul_f32 v[28:29], v[172:173], v[28:29]
	v_pk_mul_f32 v[54:55], v[54:55], v[26:27]
	v_pk_mul_f32 v[26:27], v[172:173], v[24:25]
	v_cvt_pk_bf16_f32 v24, v28, v29
	v_cvt_pk_bf16_f32 v25, v30, v31
	v_cvt_pk_bf16_f32 v26, v26, v27
	v_cvt_pk_bf16_f32 v27, v54, v55
	s_and_b64 vcc, exec, s[6:7]
	global_store_dwordx4 v[52:53], v[24:27], off nt
	s_cbranch_vccz .LBB0_245
	s_and_b64 vcc, exec, s[8:9]
	s_mov_b64 s[12:13], -1
	s_cbranch_vccz .LBB0_248

.LBB0_243:
	s_waitcnt lgkmcnt(7)
	v_mov_b32_e32 v26, v172
	s_waitcnt lgkmcnt(5)
	v_mov_b32_e32 v27, v172
	v_pk_mul_f32 v[22:23], v[26:27], v[22:23]
	v_pk_mul_f32 v[20:21], v[172:173], v[20:21]
	v_pk_mul_f32 v[26:27], v[26:27], v[18:19]
	v_pk_mul_f32 v[18:19], v[172:173], v[16:17]
	v_cvt_pk_bf16_f32 v16, v20, v21
	v_cvt_pk_bf16_f32 v17, v22, v23
	v_cvt_pk_bf16_f32 v18, v18, v19
	v_cvt_pk_bf16_f32 v19, v26, v27
	s_waitcnt vmcnt(2)
	v_add_u32_e32 v38, 0xb0, v206
	s_and_b64 vcc, exec, s[6:7]
	v_cmp_gt_i32_e64 s[12:13], s63, v206
	s_waitcnt lgkmcnt(4)
	global_store_dwordx4 v[24:25], v[16:19], off nt
	s_cbranch_vccnz .LBB0_249
	s_nop 0
	v_cndmask_b32_e64 v16, v202, v203, s[12:13]
	v_and_b32_e32 v16, v16, v38
	v_lshlrev_b32_e32 v16, 6, v16
	global_load_dwordx4 v[24:27], v16, s[16:17]
	s_waitcnt lgkmcnt(0)
	global_load_dwordx4 v[28:31], v16, s[16:17] offset:16
	global_load_dwordx4 v[20:23], v16, s[16:17] offset:32
	s_nop 0
	global_load_dwordx4 v[16:19], v16, s[16:17] offset:48
	s_and_b64 vcc, exec, s[10:11]
	s_waitcnt vmcnt(6)
	v_mov_b64_e32 v[32:33], 0
	s_cbranch_vccz .LBB0_250
	s_branch .LBB0_251

.LBB0_259:
	v_mov_b32_e32 v38, v172
	s_waitcnt lgkmcnt(2)
	v_mov_b32_e32 v39, v172
	v_pk_mul_f32 v[14:15], v[38:39], v[14:15]
	v_pk_mul_f32 v[12:13], v[172:173], v[12:13]
	v_pk_mul_f32 v[38:39], v[38:39], v[10:11]
	v_pk_mul_f32 v[10:11], v[172:173], v[8:9]
	v_cvt_pk_bf16_f32 v8, v12, v13
	v_cvt_pk_bf16_f32 v9, v14, v15
	v_cvt_pk_bf16_f32 v10, v10, v11
	v_cvt_pk_bf16_f32 v11, v38, v39
	s_and_b64 vcc, exec, s[6:7]
	global_store_dwordx4 v[36:37], v[8:11], off nt
	s_cbranch_vccz .LBB0_266
	s_and_b64 vcc, exec, s[8:9]
	s_mov_b64 s[6:7], -1
	s_cbranch_vccz .LBB0_269

.LBB0_263:
	s_waitcnt lgkmcnt(7)
	v_mov_b32_e32 v10, v172
	s_waitcnt lgkmcnt(5)
	v_mov_b32_e32 v11, v172
	v_pk_mul_f32 v[6:7], v[10:11], v[6:7]
	v_pk_mul_f32 v[4:5], v[172:173], v[4:5]
	v_pk_mul_f32 v[2:3], v[10:11], v[2:3]
	v_pk_mul_f32 v[0:1], v[172:173], v[0:1]
	v_cvt_pk_bf16_f32 v4, v4, v5
	v_cvt_pk_bf16_f32 v5, v6, v7
	v_cvt_pk_bf16_f32 v6, v0, v1
	v_cvt_pk_bf16_f32 v7, v2, v3
	s_andn2_b64 vcc, exec, s[4:5]
	s_mov_b64 s[4:5], -1
	s_waitcnt lgkmcnt(4)
	global_store_dwordx4 v[8:9], v[4:7], off nt
	s_cbranch_vccnz .LBB0_94
	s_andn2_b64 vcc, exec, s[22:23]
	s_cbranch_vccnz .LBB0_93
	s_barrier
	s_branch .LBB0_93

.LBB0_646:
	v_mul_f32_e32 v161, v125, v125
	v_mul_f32_e32 v162, v127, v127
	v_fmac_f32_e32 v161, v124, v124
	v_fmac_f32_e32 v162, v126, v126
	v_cvt_pk_bf16_f32 v124, v124, v125
	v_cvt_pk_bf16_f32 v125, v126, v127
	v_mul_f32_e32 v126, v117, v117
	v_mul_f32_e32 v127, v119, v119
	v_fmac_f32_e32 v126, v116, v116
	v_fmac_f32_e32 v127, v118, v118
	v_add_f32_e32 v161, v161, v162
	v_mul_f32_e32 v162, v121, v121
	v_add_f32_e32 v126, v126, v127
	v_mul_f32_e32 v127, v113, v113
	v_and_b32_e32 v159, 64, v158
	v_fmac_f32_e32 v162, v120, v120
	v_fmac_f32_e32 v127, v112, v112
	v_xor_b32_e32 v153, 16, v158
	v_add_u32_e32 v159, 64, v159
	v_add_f32_e32 v161, v161, v162
	v_mul_f32_e32 v162, v123, v123
	v_add_f32_e32 v126, v126, v127
	v_mul_f32_e32 v127, v115, v115
	v_cmp_lt_i32_e32 vcc, v153, v159
	v_fmac_f32_e32 v162, v122, v122
	v_fmac_f32_e32 v127, v114, v114
	v_cndmask_b32_e32 v153, v158, v153, vcc
	v_add_f32_e32 v161, v162, v161
	v_add_f32_e32 v126, v127, v126
	v_lshlrev_b32_e32 v160, 2, v153
	v_add_f32_e32 v161, v161, v126
	ds_bpermute_b32 v162, v160, v161
	v_xor_b32_e32 v153, 32, v158
	v_cmp_lt_i32_e32 vcc, v153, v159
	v_cvt_pk_bf16_f32 v126, v120, v121
	v_cvt_pk_bf16_f32 v120, v116, v117
	v_cndmask_b32_e32 v153, v158, v153, vcc
	v_lshlrev_b32_e32 v159, 2, v153
	s_waitcnt lgkmcnt(0)
	v_add_f32_e32 v116, v161, v162
	v_lshl_add_u32 v152, s28, 8, v147
	ds_bpermute_b32 v117, v159, v116
	v_ashrrev_i32_e32 v153, 31, v152
	v_lshl_or_b32 v150, s10, 8, v154
	v_lshlrev_b64 v[164:165], 11, v[152:153]
	v_ashrrev_i32_e32 v151, 31, v150
	s_lshl_b32 s28, s10, 2
	v_lshl_add_u64 v[164:165], s[82:83], 0, v[164:165]
	s_ashr_i32 s29, s28, 31
	v_lshl_add_u64 v[164:165], v[150:151], 1, v[164:165]
	v_cvt_pk_bf16_f32 v127, v122, v123
	v_cvt_pk_bf16_f32 v121, v118, v119
	v_cvt_pk_bf16_f32 v122, v112, v113
	v_cvt_pk_bf16_f32 v123, v114, v115
	global_store_dwordx4 v[164:165], v[124:127], off nt
	global_store_dwordx4 v[164:165], v[120:123], off offset:256 nt
	s_and_saveexec_b64 s[30:31], s[4:5]
	v_readlane_b32 s52, v254, 2
	v_readlane_b32 s53, v254, 3
	v_readlane_b32 s54, v254, 4
	v_readlane_b32 s55, v254, 5
	v_readlane_b32 s56, v254, 6
	v_readlane_b32 s57, v254, 7
	v_readlane_b32 s58, v254, 8
	v_readlane_b32 s59, v254, 9
	v_readlane_b32 s60, v254, 10
	v_readlane_b32 s61, v254, 11
	v_readlane_b32 s62, v254, 12
	v_readlane_b32 s63, v254, 13
	v_readlane_b32 s64, v254, 14
	v_readlane_b32 s65, v254, 15
	v_readlane_b32 s66, v254, 16
	v_readlane_b32 s67, v254, 17
	s_cbranch_execz .LBB0_648
	v_lshlrev_b64 v[112:113], 6, v[152:153]
	v_lshl_add_u64 v[112:113], s[14:15], 0, v[112:113]
	v_lshl_add_u64 v[112:113], s[28:29], 2, v[112:113]
	s_lshl_b32 s10, s40, 2
	s_waitcnt lgkmcnt(0)
	v_add_f32_e32 v114, v116, v117
	v_lshl_add_u64 v[112:113], v[112:113], 0, s[10:11]
	global_store_dword v[112:113], v114, off
.LBB0_648:
	s_or_b64 exec, exec, s[30:31]
	v_mul_f32_e32 v116, v109, v109
	s_waitcnt lgkmcnt(0)
	v_mul_f32_e32 v117, v111, v111
	v_fmac_f32_e32 v116, v108, v108
	v_fmac_f32_e32 v117, v110, v110
	v_cvt_pk_bf16_f32 v108, v108, v109
	v_cvt_pk_bf16_f32 v109, v110, v111
	v_mul_f32_e32 v110, v101, v101
	v_mul_f32_e32 v111, v103, v103
	v_fmac_f32_e32 v110, v100, v100
	v_fmac_f32_e32 v111, v102, v102
	v_add_f32_e32 v116, v116, v117
	v_mul_f32_e32 v117, v105, v105
	v_add_f32_e32 v110, v110, v111
	v_mul_f32_e32 v111, v97, v97
	v_fmac_f32_e32 v117, v104, v104
	v_fmac_f32_e32 v111, v96, v96
	v_add_f32_e32 v116, v116, v117
	v_mul_f32_e32 v117, v107, v107
	v_add_f32_e32 v110, v110, v111
	v_mul_f32_e32 v111, v99, v99
	v_fmac_f32_e32 v117, v106, v106
	v_fmac_f32_e32 v111, v98, v98
	v_add_f32_e32 v116, v117, v116
	v_add_f32_e32 v110, v111, v110
	v_add_f32_e32 v116, v116, v110
	ds_bpermute_b32 v117, v160, v116
	v_cvt_pk_bf16_f32 v110, v104, v105
	v_cvt_pk_bf16_f32 v104, v100, v101
	v_or_b32_e32 v112, 16, v152
	v_ashrrev_i32_e32 v113, 31, v112
	s_waitcnt lgkmcnt(0)
	v_add_f32_e32 v100, v116, v117
	ds_bpermute_b32 v101, v159, v100
	v_lshlrev_b64 v[114:115], 11, v[112:113]
	v_lshl_add_u64 v[114:115], s[82:83], 0, v[114:115]
	v_lshl_add_u64 v[114:115], v[150:151], 1, v[114:115]
	v_cvt_pk_bf16_f32 v111, v106, v107
	v_cvt_pk_bf16_f32 v105, v102, v103
	v_cvt_pk_bf16_f32 v106, v96, v97
	v_cvt_pk_bf16_f32 v107, v98, v99
	global_store_dwordx4 v[114:115], v[108:111], off nt
	global_store_dwordx4 v[114:115], v[104:107], off offset:256 nt
	s_and_saveexec_b64 s[30:31], s[4:5]
	s_cbranch_execz .LBB0_650
	v_lshlrev_b64 v[96:97], 6, v[112:113]
	v_lshl_add_u64 v[96:97], s[14:15], 0, v[96:97]
	v_lshl_add_u64 v[96:97], s[28:29], 2, v[96:97]
	s_lshl_b32 s10, s40, 2
	s_waitcnt lgkmcnt(0)
	v_add_f32_e32 v98, v100, v101
	v_lshl_add_u64 v[96:97], v[96:97], 0, s[10:11]
	global_store_dword v[96:97], v98, off
.LBB0_650:
	s_or_b64 exec, exec, s[30:31]
	v_mul_f32_e32 v100, v93, v93
	s_waitcnt lgkmcnt(0)
	v_mul_f32_e32 v101, v95, v95
	v_fmac_f32_e32 v100, v92, v92
	v_fmac_f32_e32 v101, v94, v94
	v_cvt_pk_bf16_f32 v92, v92, v93
	v_cvt_pk_bf16_f32 v93, v94, v95
	v_mul_f32_e32 v94, v85, v85
	v_mul_f32_e32 v95, v87, v87
	v_fmac_f32_e32 v94, v84, v84
	v_fmac_f32_e32 v95, v86, v86
	v_add_f32_e32 v100, v100, v101
	v_mul_f32_e32 v101, v89, v89
	v_add_f32_e32 v94, v94, v95
	v_mul_f32_e32 v95, v81, v81
	v_fmac_f32_e32 v101, v88, v88
	v_fmac_f32_e32 v95, v80, v80
	v_add_f32_e32 v100, v100, v101
	v_mul_f32_e32 v101, v91, v91
	v_add_f32_e32 v94, v94, v95
	v_mul_f32_e32 v95, v83, v83
	v_fmac_f32_e32 v101, v90, v90
	v_fmac_f32_e32 v95, v82, v82
	v_add_f32_e32 v100, v101, v100
	v_add_f32_e32 v94, v95, v94
	v_add_f32_e32 v100, v100, v94
	ds_bpermute_b32 v101, v160, v100
	v_cvt_pk_bf16_f32 v94, v88, v89
	v_cvt_pk_bf16_f32 v88, v84, v85
	v_or_b32_e32 v96, 32, v152
	v_ashrrev_i32_e32 v97, 31, v96
	s_waitcnt lgkmcnt(0)
	v_add_f32_e32 v84, v100, v101
	ds_bpermute_b32 v85, v159, v84
	v_lshlrev_b64 v[98:99], 11, v[96:97]
	v_lshl_add_u64 v[98:99], s[82:83], 0, v[98:99]
	v_lshl_add_u64 v[98:99], v[150:151], 1, v[98:99]
	v_cvt_pk_bf16_f32 v95, v90, v91
	v_cvt_pk_bf16_f32 v89, v86, v87
	v_cvt_pk_bf16_f32 v90, v80, v81
	v_cvt_pk_bf16_f32 v91, v82, v83
	global_store_dwordx4 v[98:99], v[92:95], off nt
	global_store_dwordx4 v[98:99], v[88:91], off offset:256 nt
	s_and_saveexec_b64 s[30:31], s[4:5]
	s_cbranch_execz .LBB0_652
	v_lshlrev_b64 v[80:81], 6, v[96:97]
	v_lshl_add_u64 v[80:81], s[14:15], 0, v[80:81]
	v_lshl_add_u64 v[80:81], s[28:29], 2, v[80:81]
	s_lshl_b32 s10, s40, 2
	s_waitcnt lgkmcnt(0)
	v_add_f32_e32 v82, v84, v85
	v_lshl_add_u64 v[80:81], v[80:81], 0, s[10:11]
	global_store_dword v[80:81], v82, off
.LBB0_652:
	s_or_b64 exec, exec, s[30:31]
	v_mul_f32_e32 v84, v77, v77
	s_waitcnt lgkmcnt(0)
	v_mul_f32_e32 v85, v79, v79
	v_fmac_f32_e32 v84, v76, v76
	v_fmac_f32_e32 v85, v78, v78
	v_cvt_pk_bf16_f32 v76, v76, v77
	v_cvt_pk_bf16_f32 v77, v78, v79
	v_mul_f32_e32 v78, v69, v69
	v_mul_f32_e32 v79, v71, v71
	v_fmac_f32_e32 v78, v68, v68
	v_fmac_f32_e32 v79, v70, v70
	v_add_f32_e32 v84, v84, v85
	v_mul_f32_e32 v85, v73, v73
	v_add_f32_e32 v78, v78, v79
	v_mul_f32_e32 v79, v65, v65
	v_fmac_f32_e32 v85, v72, v72
	v_fmac_f32_e32 v79, v64, v64
	v_add_f32_e32 v84, v84, v85
	v_mul_f32_e32 v85, v75, v75
	v_add_f32_e32 v78, v78, v79
	v_mul_f32_e32 v79, v67, v67
	v_fmac_f32_e32 v85, v74, v74
	v_fmac_f32_e32 v79, v66, v66
	v_add_f32_e32 v84, v85, v84
	v_add_f32_e32 v78, v79, v78
	v_add_f32_e32 v84, v84, v78
	ds_bpermute_b32 v85, v160, v84
	v_cvt_pk_bf16_f32 v78, v72, v73
	v_cvt_pk_bf16_f32 v72, v68, v69
	v_or_b32_e32 v80, 48, v152
	v_ashrrev_i32_e32 v81, 31, v80
	s_waitcnt lgkmcnt(0)
	v_add_f32_e32 v68, v84, v85
	ds_bpermute_b32 v69, v159, v68
	v_lshlrev_b64 v[82:83], 11, v[80:81]
	v_lshl_add_u64 v[82:83], s[82:83], 0, v[82:83]
	v_lshl_add_u64 v[82:83], v[150:151], 1, v[82:83]
	v_cvt_pk_bf16_f32 v79, v74, v75
	v_cvt_pk_bf16_f32 v73, v70, v71
	v_cvt_pk_bf16_f32 v74, v64, v65
	v_cvt_pk_bf16_f32 v75, v66, v67
	global_store_dwordx4 v[82:83], v[76:79], off nt
	global_store_dwordx4 v[82:83], v[72:75], off offset:256 nt
	s_and_saveexec_b64 s[30:31], s[4:5]
	s_cbranch_execz .LBB0_654
	v_lshlrev_b64 v[64:65], 6, v[80:81]
	v_lshl_add_u64 v[64:65], s[14:15], 0, v[64:65]
	v_lshl_add_u64 v[64:65], s[28:29], 2, v[64:65]
	s_lshl_b32 s10, s40, 2
	s_waitcnt lgkmcnt(0)
	v_add_f32_e32 v66, v68, v69
	v_lshl_add_u64 v[64:65], v[64:65], 0, s[10:11]
	global_store_dword v[64:65], v66, off
.LBB0_654:
	s_or_b64 exec, exec, s[30:31]
	v_mul_f32_e32 v68, v61, v61
	s_waitcnt lgkmcnt(0)
	v_mul_f32_e32 v69, v63, v63
	v_fmac_f32_e32 v68, v60, v60
	v_fmac_f32_e32 v69, v62, v62
	v_cvt_pk_bf16_f32 v60, v60, v61
	v_cvt_pk_bf16_f32 v61, v62, v63
	v_mul_f32_e32 v62, v53, v53
	v_mul_f32_e32 v63, v55, v55
	v_fmac_f32_e32 v62, v52, v52
	v_fmac_f32_e32 v63, v54, v54
	v_add_f32_e32 v68, v68, v69
	v_mul_f32_e32 v69, v57, v57
	v_add_f32_e32 v62, v62, v63
	v_mul_f32_e32 v63, v49, v49
	v_fmac_f32_e32 v69, v56, v56
	v_fmac_f32_e32 v63, v48, v48
	v_add_f32_e32 v68, v68, v69
	v_mul_f32_e32 v69, v59, v59
	v_add_f32_e32 v62, v62, v63
	v_mul_f32_e32 v63, v51, v51
	v_fmac_f32_e32 v69, v58, v58
	v_fmac_f32_e32 v63, v50, v50
	v_add_f32_e32 v68, v69, v68
	v_add_f32_e32 v62, v63, v62
	v_add_f32_e32 v68, v68, v62
	ds_bpermute_b32 v69, v160, v68
	v_cvt_pk_bf16_f32 v62, v56, v57
	v_cvt_pk_bf16_f32 v56, v52, v53
	v_add_u32_e32 v64, 0x80, v152
	v_ashrrev_i32_e32 v65, 31, v64
	s_waitcnt lgkmcnt(0)
	v_add_f32_e32 v52, v68, v69
	ds_bpermute_b32 v53, v159, v52
	v_lshlrev_b64 v[66:67], 11, v[64:65]
	v_lshl_add_u64 v[66:67], s[82:83], 0, v[66:67]
	v_lshl_add_u64 v[66:67], v[150:151], 1, v[66:67]
	v_cvt_pk_bf16_f32 v63, v58, v59
	v_cvt_pk_bf16_f32 v57, v54, v55
	v_cvt_pk_bf16_f32 v58, v48, v49
	v_cvt_pk_bf16_f32 v59, v50, v51
	global_store_dwordx4 v[66:67], v[60:63], off nt
	global_store_dwordx4 v[66:67], v[56:59], off offset:256 nt
	s_and_saveexec_b64 s[30:31], s[4:5]
	s_cbranch_execz .LBB0_656
	v_lshlrev_b64 v[48:49], 6, v[64:65]
	v_lshl_add_u64 v[48:49], s[14:15], 0, v[48:49]
	v_lshl_add_u64 v[48:49], s[28:29], 2, v[48:49]
	s_lshl_b32 s10, s40, 2
	s_waitcnt lgkmcnt(0)
	v_add_f32_e32 v50, v52, v53
	v_lshl_add_u64 v[48:49], v[48:49], 0, s[10:11]
	global_store_dword v[48:49], v50, off
.LBB0_656:
	s_or_b64 exec, exec, s[30:31]
	v_mul_f32_e32 v52, v45, v45
	s_waitcnt lgkmcnt(0)
	v_mul_f32_e32 v53, v47, v47
	v_fmac_f32_e32 v52, v44, v44
	v_fmac_f32_e32 v53, v46, v46
	v_cvt_pk_bf16_f32 v44, v44, v45
	v_cvt_pk_bf16_f32 v45, v46, v47
	v_mul_f32_e32 v46, v37, v37
	v_mul_f32_e32 v47, v39, v39
	v_fmac_f32_e32 v46, v36, v36
	v_fmac_f32_e32 v47, v38, v38
	v_add_f32_e32 v52, v52, v53
	v_mul_f32_e32 v53, v41, v41
	v_add_f32_e32 v46, v46, v47
	v_mul_f32_e32 v47, v33, v33
	v_fmac_f32_e32 v53, v40, v40
	v_fmac_f32_e32 v47, v32, v32
	v_add_f32_e32 v52, v52, v53
	v_mul_f32_e32 v53, v43, v43
	v_add_f32_e32 v46, v46, v47
	v_mul_f32_e32 v47, v35, v35
	v_fmac_f32_e32 v53, v42, v42
	v_fmac_f32_e32 v47, v34, v34
	v_add_f32_e32 v52, v53, v52
	v_add_f32_e32 v46, v47, v46
	v_add_f32_e32 v52, v52, v46
	ds_bpermute_b32 v53, v160, v52
	v_cvt_pk_bf16_f32 v46, v40, v41
	v_cvt_pk_bf16_f32 v40, v36, v37
	v_add_u32_e32 v48, 0x90, v152
	v_ashrrev_i32_e32 v49, 31, v48
	s_waitcnt lgkmcnt(0)
	v_add_f32_e32 v36, v52, v53
	ds_bpermute_b32 v37, v159, v36
	v_lshlrev_b64 v[50:51], 11, v[48:49]
	v_lshl_add_u64 v[50:51], s[82:83], 0, v[50:51]
	v_lshl_add_u64 v[50:51], v[150:151], 1, v[50:51]
	v_cvt_pk_bf16_f32 v47, v42, v43
	v_cvt_pk_bf16_f32 v41, v38, v39
	v_cvt_pk_bf16_f32 v42, v32, v33
	v_cvt_pk_bf16_f32 v43, v34, v35
	global_store_dwordx4 v[50:51], v[44:47], off nt
	global_store_dwordx4 v[50:51], v[40:43], off offset:256 nt
	s_and_saveexec_b64 s[30:31], s[4:5]
	s_cbranch_execz .LBB0_658
	v_lshlrev_b64 v[32:33], 6, v[48:49]
	v_lshl_add_u64 v[32:33], s[14:15], 0, v[32:33]
	v_lshl_add_u64 v[32:33], s[28:29], 2, v[32:33]
	s_lshl_b32 s10, s40, 2
	s_waitcnt lgkmcnt(0)
	v_add_f32_e32 v34, v36, v37
	v_lshl_add_u64 v[32:33], v[32:33], 0, s[10:11]
	global_store_dword v[32:33], v34, off
.LBB0_658:
	s_or_b64 exec, exec, s[30:31]
	v_mul_f32_e32 v36, v29, v29
	s_waitcnt lgkmcnt(0)
	v_mul_f32_e32 v37, v31, v31
	v_fmac_f32_e32 v36, v28, v28
	v_fmac_f32_e32 v37, v30, v30
	v_cvt_pk_bf16_f32 v28, v28, v29
	v_cvt_pk_bf16_f32 v29, v30, v31
	v_mul_f32_e32 v30, v21, v21
	v_mul_f32_e32 v31, v23, v23
	v_fmac_f32_e32 v30, v20, v20
	v_fmac_f32_e32 v31, v22, v22
	v_add_f32_e32 v36, v36, v37
	v_mul_f32_e32 v37, v25, v25
	v_add_f32_e32 v30, v30, v31
	v_mul_f32_e32 v31, v17, v17
	v_fmac_f32_e32 v37, v24, v24
	v_fmac_f32_e32 v31, v16, v16
	v_add_f32_e32 v36, v36, v37
	v_mul_f32_e32 v37, v27, v27
	v_add_f32_e32 v30, v30, v31
	v_mul_f32_e32 v31, v19, v19
	v_fmac_f32_e32 v37, v26, v26
	v_fmac_f32_e32 v31, v18, v18
	v_add_f32_e32 v36, v37, v36
	v_add_f32_e32 v30, v31, v30
	v_add_f32_e32 v36, v36, v30
	ds_bpermute_b32 v37, v160, v36
	v_cvt_pk_bf16_f32 v30, v24, v25
	v_cvt_pk_bf16_f32 v24, v20, v21
	v_add_u32_e32 v32, 0xa0, v152
	v_ashrrev_i32_e32 v33, 31, v32
	s_waitcnt lgkmcnt(0)
	v_add_f32_e32 v20, v36, v37
	ds_bpermute_b32 v21, v159, v20
	v_lshlrev_b64 v[34:35], 11, v[32:33]
	v_lshl_add_u64 v[34:35], s[82:83], 0, v[34:35]
	v_lshl_add_u64 v[34:35], v[150:151], 1, v[34:35]
	v_cvt_pk_bf16_f32 v31, v26, v27
	v_cvt_pk_bf16_f32 v25, v22, v23
	v_cvt_pk_bf16_f32 v26, v16, v17
	v_cvt_pk_bf16_f32 v27, v18, v19
	global_store_dwordx4 v[34:35], v[28:31], off nt
	global_store_dwordx4 v[34:35], v[24:27], off offset:256 nt
	s_and_saveexec_b64 s[30:31], s[4:5]
	s_cbranch_execz .LBB0_660
	v_lshlrev_b64 v[16:17], 6, v[32:33]
	v_lshl_add_u64 v[16:17], s[14:15], 0, v[16:17]
	v_lshl_add_u64 v[16:17], s[28:29], 2, v[16:17]
	s_lshl_b32 s10, s40, 2
	s_waitcnt lgkmcnt(0)
	v_add_f32_e32 v18, v20, v21
	v_lshl_add_u64 v[16:17], v[16:17], 0, s[10:11]
	global_store_dword v[16:17], v18, off
.LBB0_660:
	s_or_b64 exec, exec, s[30:31]
	v_mul_f32_e32 v20, v13, v13
	s_waitcnt lgkmcnt(0)
	v_mul_f32_e32 v21, v15, v15
	v_fmac_f32_e32 v20, v12, v12
	v_fmac_f32_e32 v21, v14, v14
	v_cvt_pk_bf16_f32 v12, v12, v13
	v_cvt_pk_bf16_f32 v13, v14, v15
	v_mul_f32_e32 v14, v5, v5
	v_mul_f32_e32 v15, v7, v7
	v_fmac_f32_e32 v14, v4, v4
	v_fmac_f32_e32 v15, v6, v6
	v_add_f32_e32 v20, v20, v21
	v_mul_f32_e32 v21, v9, v9
	v_add_f32_e32 v14, v14, v15
	v_mul_f32_e32 v15, v1, v1
	v_fmac_f32_e32 v21, v8, v8
	v_fmac_f32_e32 v15, v0, v0
	v_add_f32_e32 v20, v20, v21
	v_mul_f32_e32 v21, v11, v11
	v_add_f32_e32 v14, v14, v15
	v_mul_f32_e32 v15, v3, v3
	v_fmac_f32_e32 v21, v10, v10
	v_fmac_f32_e32 v15, v2, v2
	v_add_f32_e32 v20, v21, v20
	v_add_f32_e32 v14, v15, v14
	v_add_f32_e32 v20, v20, v14
	ds_bpermute_b32 v21, v160, v20
	v_cvt_pk_bf16_f32 v14, v8, v9
	v_cvt_pk_bf16_f32 v8, v4, v5
	v_add_u32_e32 v16, 0xb0, v152
	v_ashrrev_i32_e32 v17, 31, v16
	s_waitcnt lgkmcnt(0)
	v_add_f32_e32 v4, v20, v21
	ds_bpermute_b32 v5, v159, v4
	v_lshlrev_b64 v[18:19], 11, v[16:17]
	v_lshl_add_u64 v[18:19], s[82:83], 0, v[18:19]
	v_lshl_add_u64 v[18:19], v[150:151], 1, v[18:19]
	v_cvt_pk_bf16_f32 v15, v10, v11
	v_cvt_pk_bf16_f32 v9, v6, v7
	v_cvt_pk_bf16_f32 v10, v0, v1
	v_cvt_pk_bf16_f32 v11, v2, v3
	global_store_dwordx4 v[18:19], v[12:15], off nt
	global_store_dwordx4 v[18:19], v[8:11], off offset:256 nt
	s_and_saveexec_b64 s[30:31], s[4:5]
	s_cbranch_execz .LBB0_662
	v_lshlrev_b64 v[0:1], 6, v[16:17]
	v_lshl_add_u64 v[0:1], s[14:15], 0, v[0:1]
	v_lshl_add_u64 v[0:1], s[28:29], 2, v[0:1]
	s_lshl_b32 s10, s40, 2
	s_waitcnt lgkmcnt(0)
	v_add_f32_e32 v2, v4, v5
	v_lshl_add_u64 v[0:1], v[0:1], 0, s[10:11]
	global_store_dword v[0:1], v2, off

.LBB0_860:
	v_mul_f32_e32 v156, 0xbfb8aa3b, v124
	v_mul_f32_e32 v157, 0xbfb8aa3b, v120
	v_mul_f32_e32 v158, 0xbfb8aa3b, v125
	v_exp_f32_e32 v156, v156
	v_exp_f32_e32 v157, v157
	v_exp_f32_e32 v158, v158
	v_lshl_or_b32 v154, s45, 7, v149
	v_add_f32_e32 v156, 1.0, v156
	v_add_f32_e32 v159, 1.0, v157
	v_add_f32_e32 v157, 1.0, v158
	v_rcp_f32_e32 v156, v156
	v_rcp_f32_e32 v157, v157
	v_mul_f32_e32 v158, 0xbfb8aa3b, v121
	v_exp_f32_e32 v160, v158
	v_rcp_f32_e32 v158, v159
	v_pk_mul_f32 v[124:125], v[124:125], v[156:157]
	v_mul_f32_e32 v156, 0xbfb8aa3b, v127
	v_pk_mul_f32 v[116:117], v[124:125], v[116:117]
	v_add_f32_e32 v124, 1.0, v160
	v_rcp_f32_e32 v159, v124
	v_mul_f32_e32 v125, 0xbfb8aa3b, v122
	v_mul_f32_e32 v124, 0xbfb8aa3b, v126
	v_exp_f32_e32 v125, v125
	v_exp_f32_e32 v124, v124
	v_exp_f32_e32 v157, v156
	v_mul_f32_e32 v156, 0xbfb8aa3b, v123
	v_pk_mul_f32 v[120:121], v[120:121], v[158:159]
	v_exp_f32_e32 v158, v156
	v_add_f32_e32 v125, 1.0, v125
	v_add_f32_e32 v124, 1.0, v124
	v_rcp_f32_e32 v156, v125
	v_add_f32_e32 v125, 1.0, v157
	v_rcp_f32_e32 v124, v124
	v_rcp_f32_e32 v125, v125
	v_add_f32_e32 v157, 1.0, v158
	v_rcp_f32_e32 v157, v157
	v_pk_mul_f32 v[112:113], v[120:121], v[112:113]
	v_pk_mul_f32 v[120:121], v[126:127], v[124:125]
	v_lshl_add_u32 v153, s24, 8, v129
	v_pk_mul_f32 v[118:119], v[120:121], v[118:119]
	v_pk_mul_f32 v[120:121], v[122:123], v[156:157]
	v_ashrrev_i32_e32 v155, 31, v154
	v_pk_mul_f32 v[114:115], v[120:121], v[114:115]
	v_cvt_pk_bf16_f32 v116, v116, v117
	v_cvt_pk_bf16_f32 v117, v118, v119
	v_cvt_pk_bf16_f32 v118, v112, v113
	v_mov_b64_e32 v[112:113], s[10:11]
	v_cvt_pk_bf16_f32 v119, v114, v115
	v_mad_i64_i32 v[120:121], s[26:27], v153, s44, v[112:113]
	v_lshlrev_b64 v[114:115], 1, v[154:155]
	v_lshl_add_u64 v[120:121], v[120:121], 0, v[114:115]
	global_store_dwordx4 v[120:121], v[116:119], off nt
	s_andn2_b64 vcc, exec, s[4:5]
	s_mov_b64 s[4:5], -1
	v_mul_f32_e32 v116, 0xbfb8aa3b, v108
	v_mul_f32_e32 v117, 0xbfb8aa3b, v104
	v_mul_f32_e32 v118, 0xbfb8aa3b, v109
	v_exp_f32_e32 v116, v116
	v_exp_f32_e32 v117, v117
	v_exp_f32_e32 v118, v118
	v_add_f32_e32 v116, 1.0, v116
	v_add_f32_e32 v119, 1.0, v117
	v_add_f32_e32 v117, 1.0, v118
	v_rcp_f32_e32 v116, v116
	v_rcp_f32_e32 v117, v117
	v_mul_f32_e32 v118, 0xbfb8aa3b, v105
	v_exp_f32_e32 v120, v118
	v_rcp_f32_e32 v118, v119
	v_pk_mul_f32 v[108:109], v[108:109], v[116:117]
	v_mul_f32_e32 v116, 0xbfb8aa3b, v111
	v_pk_mul_f32 v[100:101], v[108:109], v[100:101]
	v_add_f32_e32 v108, 1.0, v120
	v_rcp_f32_e32 v119, v108
	v_mul_f32_e32 v109, 0xbfb8aa3b, v106
	v_mul_f32_e32 v108, 0xbfb8aa3b, v110
	v_exp_f32_e32 v109, v109
	v_exp_f32_e32 v108, v108
	v_exp_f32_e32 v117, v116
	v_mul_f32_e32 v116, 0xbfb8aa3b, v107
	v_pk_mul_f32 v[104:105], v[104:105], v[118:119]
	v_exp_f32_e32 v118, v116
	v_add_f32_e32 v109, 1.0, v109
	v_add_f32_e32 v108, 1.0, v108
	v_rcp_f32_e32 v116, v109
	v_add_f32_e32 v109, 1.0, v117
	v_rcp_f32_e32 v108, v108
	v_rcp_f32_e32 v109, v109
	v_add_f32_e32 v117, 1.0, v118
	v_rcp_f32_e32 v117, v117
	v_pk_mul_f32 v[104:105], v[104:105], v[96:97]
	v_pk_mul_f32 v[96:97], v[110:111], v[108:109]
	v_or_b32_e32 v108, 16, v153
	v_pk_mul_f32 v[102:103], v[96:97], v[102:103]
	v_pk_mul_f32 v[96:97], v[106:107], v[116:117]
	s_nop 0
	v_pk_mul_f32 v[106:107], v[96:97], v[98:99]
	v_cvt_pk_bf16_f32 v96, v100, v101
	v_mad_i64_i32 v[100:101], s[26:27], v108, s44, v[112:113]
	v_cvt_pk_bf16_f32 v97, v102, v103
	v_cvt_pk_bf16_f32 v98, v104, v105
	v_cvt_pk_bf16_f32 v99, v106, v107
	v_lshl_add_u64 v[100:101], v[100:101], 0, v[114:115]
	global_store_dwordx4 v[100:101], v[96:99], off nt
	s_nop 1
	v_mul_f32_e32 v96, 0xbfb8aa3b, v92
	v_mul_f32_e32 v97, 0xbfb8aa3b, v88
	v_mul_f32_e32 v98, 0xbfb8aa3b, v93
	v_exp_f32_e32 v96, v96
	v_exp_f32_e32 v97, v97
	v_exp_f32_e32 v98, v98
	v_add_f32_e32 v96, 1.0, v96
	v_add_f32_e32 v99, 1.0, v97
	v_add_f32_e32 v97, 1.0, v98
	v_rcp_f32_e32 v96, v96
	v_rcp_f32_e32 v97, v97
	v_mul_f32_e32 v98, 0xbfb8aa3b, v89
	v_exp_f32_e32 v100, v98
	v_rcp_f32_e32 v98, v99
	v_pk_mul_f32 v[92:93], v[92:93], v[96:97]
	v_mul_f32_e32 v96, 0xbfb8aa3b, v95
	v_pk_mul_f32 v[84:85], v[92:93], v[84:85]
	v_add_f32_e32 v92, 1.0, v100
	v_rcp_f32_e32 v99, v92
	v_mul_f32_e32 v93, 0xbfb8aa3b, v90
	v_mul_f32_e32 v92, 0xbfb8aa3b, v94
	v_exp_f32_e32 v93, v93
	v_exp_f32_e32 v92, v92
	v_exp_f32_e32 v97, v96
	v_mul_f32_e32 v96, 0xbfb8aa3b, v91
	v_pk_mul_f32 v[88:89], v[88:89], v[98:99]
	v_exp_f32_e32 v98, v96
	v_add_f32_e32 v93, 1.0, v93
	v_add_f32_e32 v92, 1.0, v92
	v_rcp_f32_e32 v96, v93
	v_add_f32_e32 v93, 1.0, v97
	v_rcp_f32_e32 v92, v92
	v_rcp_f32_e32 v93, v93
	v_add_f32_e32 v97, 1.0, v98
	v_rcp_f32_e32 v97, v97
	v_pk_mul_f32 v[88:89], v[88:89], v[80:81]
	v_pk_mul_f32 v[80:81], v[94:95], v[92:93]
	v_or_b32_e32 v92, 32, v153
	v_pk_mul_f32 v[86:87], v[80:81], v[86:87]
	v_pk_mul_f32 v[80:81], v[90:91], v[96:97]
	s_nop 0
	v_pk_mul_f32 v[90:91], v[80:81], v[82:83]
	v_cvt_pk_bf16_f32 v80, v84, v85
	v_mad_i64_i32 v[84:85], s[26:27], v92, s44, v[112:113]
	v_cvt_pk_bf16_f32 v81, v86, v87
	v_cvt_pk_bf16_f32 v82, v88, v89
	v_cvt_pk_bf16_f32 v83, v90, v91
	v_lshl_add_u64 v[84:85], v[84:85], 0, v[114:115]
	global_store_dwordx4 v[84:85], v[80:83], off nt
	s_nop 1
	v_mul_f32_e32 v80, 0xbfb8aa3b, v76
	v_mul_f32_e32 v81, 0xbfb8aa3b, v72
	v_mul_f32_e32 v82, 0xbfb8aa3b, v77
	v_exp_f32_e32 v80, v80
	v_exp_f32_e32 v81, v81
	v_exp_f32_e32 v82, v82
	v_add_f32_e32 v80, 1.0, v80
	v_add_f32_e32 v83, 1.0, v81
	v_add_f32_e32 v81, 1.0, v82
	v_rcp_f32_e32 v80, v80
	v_rcp_f32_e32 v81, v81
	v_mul_f32_e32 v82, 0xbfb8aa3b, v73
	v_exp_f32_e32 v84, v82
	v_rcp_f32_e32 v82, v83
	v_pk_mul_f32 v[76:77], v[76:77], v[80:81]
	v_mul_f32_e32 v80, 0xbfb8aa3b, v79
	v_pk_mul_f32 v[68:69], v[76:77], v[68:69]
	v_add_f32_e32 v76, 1.0, v84
	v_rcp_f32_e32 v83, v76
	v_mul_f32_e32 v77, 0xbfb8aa3b, v74
	v_mul_f32_e32 v76, 0xbfb8aa3b, v78
	v_exp_f32_e32 v77, v77
	v_exp_f32_e32 v76, v76
	v_exp_f32_e32 v81, v80
	v_mul_f32_e32 v80, 0xbfb8aa3b, v75
	v_pk_mul_f32 v[72:73], v[72:73], v[82:83]
	v_exp_f32_e32 v82, v80
	v_add_f32_e32 v77, 1.0, v77
	v_add_f32_e32 v76, 1.0, v76
	v_rcp_f32_e32 v80, v77
	v_add_f32_e32 v77, 1.0, v81
	v_rcp_f32_e32 v76, v76
	v_rcp_f32_e32 v77, v77
	v_add_f32_e32 v81, 1.0, v82
	v_rcp_f32_e32 v81, v81
	v_pk_mul_f32 v[72:73], v[72:73], v[64:65]
	v_pk_mul_f32 v[64:65], v[78:79], v[76:77]
	v_or_b32_e32 v76, 48, v153
	v_pk_mul_f32 v[70:71], v[64:65], v[70:71]
	v_pk_mul_f32 v[64:65], v[74:75], v[80:81]
	s_nop 0
	v_pk_mul_f32 v[74:75], v[64:65], v[66:67]
	v_cvt_pk_bf16_f32 v64, v68, v69
	v_mad_i64_i32 v[68:69], s[26:27], v76, s44, v[112:113]
	v_cvt_pk_bf16_f32 v65, v70, v71
	v_cvt_pk_bf16_f32 v66, v72, v73
	v_cvt_pk_bf16_f32 v67, v74, v75
	v_lshl_add_u64 v[68:69], v[68:69], 0, v[114:115]
	global_store_dwordx4 v[68:69], v[64:67], off nt
	v_add_u32_e32 v68, 0x80, v153
	s_nop 0
	v_mul_f32_e32 v64, 0xbfb8aa3b, v60
	v_mul_f32_e32 v65, 0xbfb8aa3b, v56
	v_mul_f32_e32 v66, 0xbfb8aa3b, v61
	v_exp_f32_e32 v64, v64
	v_exp_f32_e32 v65, v65
	v_exp_f32_e32 v66, v66
	v_add_f32_e32 v64, 1.0, v64
	v_add_f32_e32 v67, 1.0, v65
	v_add_f32_e32 v65, 1.0, v66
	v_rcp_f32_e32 v64, v64
	v_rcp_f32_e32 v65, v65
	v_mul_f32_e32 v66, 0xbfb8aa3b, v57
	v_exp_f32_e32 v69, v66
	v_rcp_f32_e32 v66, v67
	v_pk_mul_f32 v[60:61], v[60:61], v[64:65]
	v_mul_f32_e32 v64, 0xbfb8aa3b, v63
	v_pk_mul_f32 v[52:53], v[60:61], v[52:53]
	v_add_f32_e32 v60, 1.0, v69
	v_rcp_f32_e32 v67, v60
	v_mul_f32_e32 v61, 0xbfb8aa3b, v58
	v_mul_f32_e32 v60, 0xbfb8aa3b, v62
	v_exp_f32_e32 v61, v61
	v_exp_f32_e32 v60, v60
	v_exp_f32_e32 v65, v64
	v_mul_f32_e32 v64, 0xbfb8aa3b, v59
	v_pk_mul_f32 v[56:57], v[56:57], v[66:67]
	v_exp_f32_e32 v66, v64
	v_add_f32_e32 v61, 1.0, v61
	v_add_f32_e32 v60, 1.0, v60
	v_rcp_f32_e32 v64, v61
	v_add_f32_e32 v61, 1.0, v65
	v_rcp_f32_e32 v60, v60
	v_rcp_f32_e32 v61, v61
	v_add_f32_e32 v65, 1.0, v66
	v_rcp_f32_e32 v65, v65
	v_pk_mul_f32 v[56:57], v[56:57], v[48:49]
	v_pk_mul_f32 v[48:49], v[62:63], v[60:61]
	s_nop 0
	v_pk_mul_f32 v[54:55], v[48:49], v[54:55]
	v_pk_mul_f32 v[48:49], v[58:59], v[64:65]
	s_nop 0
	v_pk_mul_f32 v[58:59], v[48:49], v[50:51]
	v_cvt_pk_bf16_f32 v48, v52, v53
	v_mad_i64_i32 v[52:53], s[26:27], v68, s44, v[112:113]
	v_cvt_pk_bf16_f32 v49, v54, v55
	v_cvt_pk_bf16_f32 v50, v56, v57
	v_cvt_pk_bf16_f32 v51, v58, v59
	v_lshl_add_u64 v[52:53], v[52:53], 0, v[114:115]
	global_store_dwordx4 v[52:53], v[48:51], off nt
	s_nop 1
	v_mul_f32_e32 v48, 0xbfb8aa3b, v44
	v_mul_f32_e32 v49, 0xbfb8aa3b, v40
	v_mul_f32_e32 v50, 0xbfb8aa3b, v45
	v_exp_f32_e32 v48, v48
	v_exp_f32_e32 v49, v49
	v_exp_f32_e32 v50, v50
	v_add_f32_e32 v48, 1.0, v48
	v_add_f32_e32 v51, 1.0, v49
	v_add_f32_e32 v49, 1.0, v50
	v_rcp_f32_e32 v48, v48
	v_rcp_f32_e32 v49, v49
	v_mul_f32_e32 v50, 0xbfb8aa3b, v41
	v_exp_f32_e32 v52, v50
	v_rcp_f32_e32 v50, v51
	v_pk_mul_f32 v[44:45], v[44:45], v[48:49]
	v_mul_f32_e32 v48, 0xbfb8aa3b, v47
	v_pk_mul_f32 v[36:37], v[44:45], v[36:37]
	v_add_f32_e32 v44, 1.0, v52
	v_rcp_f32_e32 v51, v44
	v_mul_f32_e32 v45, 0xbfb8aa3b, v42
	v_mul_f32_e32 v44, 0xbfb8aa3b, v46
	v_exp_f32_e32 v45, v45
	v_exp_f32_e32 v44, v44
	v_exp_f32_e32 v49, v48
	v_mul_f32_e32 v48, 0xbfb8aa3b, v43
	v_pk_mul_f32 v[40:41], v[40:41], v[50:51]
	v_exp_f32_e32 v50, v48
	v_add_f32_e32 v45, 1.0, v45
	v_add_f32_e32 v44, 1.0, v44
	v_rcp_f32_e32 v48, v45
	v_add_f32_e32 v45, 1.0, v49
	v_rcp_f32_e32 v44, v44
	v_rcp_f32_e32 v45, v45
	v_add_f32_e32 v49, 1.0, v50
	v_rcp_f32_e32 v49, v49
	v_pk_mul_f32 v[40:41], v[40:41], v[32:33]
	v_pk_mul_f32 v[32:33], v[46:47], v[44:45]
	v_add_u32_e32 v44, 0x90, v153
	v_pk_mul_f32 v[38:39], v[32:33], v[38:39]
	v_pk_mul_f32 v[32:33], v[42:43], v[48:49]
	s_nop 0
	v_pk_mul_f32 v[42:43], v[32:33], v[34:35]
	v_cvt_pk_bf16_f32 v32, v36, v37
	v_mad_i64_i32 v[36:37], s[26:27], v44, s44, v[112:113]
	v_cvt_pk_bf16_f32 v33, v38, v39
	v_cvt_pk_bf16_f32 v34, v40, v41
	v_cvt_pk_bf16_f32 v35, v42, v43
	v_lshl_add_u64 v[36:37], v[36:37], 0, v[114:115]
	global_store_dwordx4 v[36:37], v[32:35], off nt
	s_nop 1
	v_mul_f32_e32 v32, 0xbfb8aa3b, v28
	v_mul_f32_e32 v33, 0xbfb8aa3b, v24
	v_mul_f32_e32 v34, 0xbfb8aa3b, v29
	v_exp_f32_e32 v32, v32
	v_exp_f32_e32 v33, v33
	v_exp_f32_e32 v34, v34
	v_add_f32_e32 v32, 1.0, v32
	v_add_f32_e32 v35, 1.0, v33
	v_add_f32_e32 v33, 1.0, v34
	v_rcp_f32_e32 v32, v32
	v_rcp_f32_e32 v33, v33
	v_mul_f32_e32 v34, 0xbfb8aa3b, v25
	v_exp_f32_e32 v36, v34
	v_rcp_f32_e32 v34, v35
	v_pk_mul_f32 v[28:29], v[28:29], v[32:33]
	v_mul_f32_e32 v32, 0xbfb8aa3b, v31
	v_pk_mul_f32 v[20:21], v[28:29], v[20:21]
	v_add_f32_e32 v28, 1.0, v36
	v_rcp_f32_e32 v35, v28
	v_mul_f32_e32 v29, 0xbfb8aa3b, v26
	v_mul_f32_e32 v28, 0xbfb8aa3b, v30
	v_exp_f32_e32 v29, v29
	v_exp_f32_e32 v28, v28
	v_exp_f32_e32 v33, v32
	v_mul_f32_e32 v32, 0xbfb8aa3b, v27
	v_pk_mul_f32 v[24:25], v[24:25], v[34:35]
	v_exp_f32_e32 v34, v32
	v_add_f32_e32 v29, 1.0, v29
	v_add_f32_e32 v28, 1.0, v28
	v_rcp_f32_e32 v32, v29
	v_add_f32_e32 v29, 1.0, v33
	v_rcp_f32_e32 v28, v28
	v_rcp_f32_e32 v29, v29
	v_add_f32_e32 v33, 1.0, v34
	v_rcp_f32_e32 v33, v33
	v_pk_mul_f32 v[24:25], v[24:25], v[16:17]
	v_pk_mul_f32 v[16:17], v[30:31], v[28:29]
	v_add_u32_e32 v28, 0xa0, v153
	v_pk_mul_f32 v[22:23], v[16:17], v[22:23]
	v_pk_mul_f32 v[16:17], v[26:27], v[32:33]
	s_nop 0
	v_pk_mul_f32 v[26:27], v[16:17], v[18:19]
	v_cvt_pk_bf16_f32 v16, v20, v21
	v_mad_i64_i32 v[20:21], s[26:27], v28, s44, v[112:113]
	v_cvt_pk_bf16_f32 v17, v22, v23
	v_cvt_pk_bf16_f32 v18, v24, v25
	v_cvt_pk_bf16_f32 v19, v26, v27
	v_lshl_add_u64 v[20:21], v[20:21], 0, v[114:115]
	global_store_dwordx4 v[20:21], v[16:19], off nt
	s_nop 1
	v_mul_f32_e32 v16, 0xbfb8aa3b, v12
	v_mul_f32_e32 v17, 0xbfb8aa3b, v8
	v_mul_f32_e32 v18, 0xbfb8aa3b, v13
	v_exp_f32_e32 v16, v16
	v_exp_f32_e32 v17, v17
	v_exp_f32_e32 v18, v18
	v_add_f32_e32 v16, 1.0, v16
	v_add_f32_e32 v19, 1.0, v17
	v_add_f32_e32 v17, 1.0, v18
	v_rcp_f32_e32 v16, v16
	v_rcp_f32_e32 v17, v17
	v_mul_f32_e32 v18, 0xbfb8aa3b, v9
	v_exp_f32_e32 v20, v18
	v_rcp_f32_e32 v18, v19
	v_pk_mul_f32 v[12:13], v[12:13], v[16:17]
	v_mul_f32_e32 v16, 0xbfb8aa3b, v15
	v_pk_mul_f32 v[4:5], v[12:13], v[4:5]
	v_add_f32_e32 v12, 1.0, v20
	v_rcp_f32_e32 v19, v12
	v_mul_f32_e32 v13, 0xbfb8aa3b, v10
	v_mul_f32_e32 v12, 0xbfb8aa3b, v14
	v_exp_f32_e32 v13, v13
	v_exp_f32_e32 v12, v12
	v_exp_f32_e32 v17, v16
	v_mul_f32_e32 v16, 0xbfb8aa3b, v11
	v_pk_mul_f32 v[8:9], v[8:9], v[18:19]
	v_exp_f32_e32 v18, v16
	v_add_f32_e32 v13, 1.0, v13
	v_add_f32_e32 v12, 1.0, v12
	v_rcp_f32_e32 v16, v13
	v_add_f32_e32 v13, 1.0, v17
	v_rcp_f32_e32 v12, v12
	v_rcp_f32_e32 v13, v13
	v_add_f32_e32 v17, 1.0, v18
	v_rcp_f32_e32 v17, v17
	v_pk_mul_f32 v[8:9], v[8:9], v[0:1]
	v_pk_mul_f32 v[0:1], v[14:15], v[12:13]
	v_add_u32_e32 v12, 0xb0, v153
	v_pk_mul_f32 v[6:7], v[0:1], v[6:7]
	v_pk_mul_f32 v[0:1], v[10:11], v[16:17]
	s_nop 0
	v_pk_mul_f32 v[10:11], v[0:1], v[2:3]
	v_cvt_pk_bf16_f32 v0, v4, v5
	v_mad_i64_i32 v[4:5], s[26:27], v12, s44, v[112:113]
	v_cvt_pk_bf16_f32 v1, v6, v7
	v_cvt_pk_bf16_f32 v2, v8, v9
	v_cvt_pk_bf16_f32 v3, v10, v11
	v_lshl_add_u64 v[4:5], v[4:5], 0, v[114:115]
	global_store_dwordx4 v[4:5], v[0:3], off nt
	s_cbranch_vccnz .LBB0_853
	s_andn2_b64 vcc, exec, s[6:7]
	s_cbranch_vccnz .LBB0_852
	s_barrier
	s_branch .LBB0_852

.LBB0_942:
	v_mul_f32_e32 v159, v125, v125
	v_mul_f32_e32 v162, v127, v127
	v_fmac_f32_e32 v159, v124, v124
	v_fmac_f32_e32 v162, v126, v126
	v_cvt_pk_bf16_f32 v124, v124, v125
	v_cvt_pk_bf16_f32 v125, v126, v127
	v_mul_f32_e32 v126, v117, v117
	v_mul_f32_e32 v127, v119, v119
	v_fmac_f32_e32 v126, v116, v116
	v_fmac_f32_e32 v127, v118, v118
	v_add_f32_e32 v159, v159, v162
	v_mul_f32_e32 v162, v121, v121
	v_add_f32_e32 v126, v126, v127
	v_mul_f32_e32 v127, v113, v113
	v_and_b32_e32 v157, 64, v156
	v_fmac_f32_e32 v162, v120, v120
	v_fmac_f32_e32 v127, v112, v112
	v_xor_b32_e32 v151, 16, v156
	v_add_u32_e32 v157, 64, v157
	v_add_f32_e32 v159, v159, v162
	v_mul_f32_e32 v162, v123, v123
	v_add_f32_e32 v126, v126, v127
	v_mul_f32_e32 v127, v115, v115
	v_cmp_lt_i32_e32 vcc, v151, v157
	v_fmac_f32_e32 v162, v122, v122
	v_fmac_f32_e32 v127, v114, v114
	v_cndmask_b32_e32 v151, v156, v151, vcc
	v_add_f32_e32 v159, v162, v159
	v_add_f32_e32 v126, v127, v126
	v_lshlrev_b32_e32 v158, 2, v151
	v_add_f32_e32 v159, v159, v126
	ds_bpermute_b32 v162, v158, v159
	v_xor_b32_e32 v151, 32, v156
	v_cmp_lt_i32_e32 vcc, v151, v157
	v_cvt_pk_bf16_f32 v126, v120, v121
	v_cvt_pk_bf16_f32 v120, v116, v117
	v_cndmask_b32_e32 v151, v156, v151, vcc
	v_lshlrev_b32_e32 v157, 2, v151
	s_waitcnt lgkmcnt(0)
	v_add_f32_e32 v116, v159, v162
	v_lshl_add_u32 v150, s47, 8, v129
	ds_bpermute_b32 v117, v157, v116
	v_ashrrev_i32_e32 v151, 31, v150
	v_lshl_or_b32 v148, s12, 8, v152
	v_lshlrev_b64 v[160:161], 11, v[150:151]
	v_ashrrev_i32_e32 v149, 31, v148
	s_lshl_b32 s24, s12, 2
	v_lshl_add_u64 v[160:161], s[82:83], 0, v[160:161]
	s_ashr_i32 s25, s24, 31
	v_lshl_add_u64 v[160:161], v[148:149], 1, v[160:161]
	v_cvt_pk_bf16_f32 v127, v122, v123
	v_cvt_pk_bf16_f32 v121, v118, v119
	v_cvt_pk_bf16_f32 v122, v112, v113
	v_cvt_pk_bf16_f32 v123, v114, v115
	global_store_dwordx4 v[160:161], v[124:127], off nt
	global_store_dwordx4 v[160:161], v[120:123], off offset:256 nt
	s_and_saveexec_b64 s[26:27], s[8:9]
	s_cbranch_execz .LBB0_944
	v_lshlrev_b64 v[112:113], 6, v[150:151]
	v_lshl_add_u64 v[112:113], s[16:17], 0, v[112:113]
	v_lshl_add_u64 v[112:113], s[24:25], 2, v[112:113]
	s_lshl_b32 s12, s36, 2
	s_waitcnt lgkmcnt(0)
	v_add_f32_e32 v114, v116, v117
	v_lshl_add_u64 v[112:113], v[112:113], 0, s[12:13]
	global_store_dword v[112:113], v114, off
.LBB0_944:
	s_or_b64 exec, exec, s[26:27]
	v_mul_f32_e32 v116, v109, v109
	s_waitcnt lgkmcnt(0)
	v_mul_f32_e32 v117, v111, v111
	v_fmac_f32_e32 v116, v108, v108
	v_fmac_f32_e32 v117, v110, v110
	v_cvt_pk_bf16_f32 v108, v108, v109
	v_cvt_pk_bf16_f32 v109, v110, v111
	v_mul_f32_e32 v110, v101, v101
	v_mul_f32_e32 v111, v103, v103
	v_fmac_f32_e32 v110, v100, v100
	v_fmac_f32_e32 v111, v102, v102
	v_add_f32_e32 v116, v116, v117
	v_mul_f32_e32 v117, v105, v105
	v_add_f32_e32 v110, v110, v111
	v_mul_f32_e32 v111, v97, v97
	v_fmac_f32_e32 v117, v104, v104
	v_fmac_f32_e32 v111, v96, v96
	v_add_f32_e32 v116, v116, v117
	v_mul_f32_e32 v117, v107, v107
	v_add_f32_e32 v110, v110, v111
	v_mul_f32_e32 v111, v99, v99
	v_fmac_f32_e32 v117, v106, v106
	v_fmac_f32_e32 v111, v98, v98
	v_add_f32_e32 v116, v117, v116
	v_add_f32_e32 v110, v111, v110
	v_add_f32_e32 v116, v116, v110
	ds_bpermute_b32 v117, v158, v116
	v_cvt_pk_bf16_f32 v110, v104, v105
	v_cvt_pk_bf16_f32 v104, v100, v101
	v_or_b32_e32 v112, 16, v150
	v_ashrrev_i32_e32 v113, 31, v112
	s_waitcnt lgkmcnt(0)
	v_add_f32_e32 v100, v116, v117
	ds_bpermute_b32 v101, v157, v100
	v_lshlrev_b64 v[114:115], 11, v[112:113]
	v_lshl_add_u64 v[114:115], s[82:83], 0, v[114:115]
	v_lshl_add_u64 v[114:115], v[148:149], 1, v[114:115]
	v_cvt_pk_bf16_f32 v111, v106, v107
	v_cvt_pk_bf16_f32 v105, v102, v103
	v_cvt_pk_bf16_f32 v106, v96, v97
	v_cvt_pk_bf16_f32 v107, v98, v99
	global_store_dwordx4 v[114:115], v[108:111], off nt
	global_store_dwordx4 v[114:115], v[104:107], off offset:256 nt
	s_and_saveexec_b64 s[26:27], s[8:9]
	s_cbranch_execz .LBB0_946
	v_lshlrev_b64 v[96:97], 6, v[112:113]
	v_lshl_add_u64 v[96:97], s[16:17], 0, v[96:97]
	v_lshl_add_u64 v[96:97], s[24:25], 2, v[96:97]
	s_lshl_b32 s12, s36, 2
	s_waitcnt lgkmcnt(0)
	v_add_f32_e32 v98, v100, v101
	v_lshl_add_u64 v[96:97], v[96:97], 0, s[12:13]
	global_store_dword v[96:97], v98, off
.LBB0_946:
	s_or_b64 exec, exec, s[26:27]
	v_mul_f32_e32 v100, v93, v93
	s_waitcnt lgkmcnt(0)
	v_mul_f32_e32 v101, v95, v95
	v_fmac_f32_e32 v100, v92, v92
	v_fmac_f32_e32 v101, v94, v94
	v_cvt_pk_bf16_f32 v92, v92, v93
	v_cvt_pk_bf16_f32 v93, v94, v95
	v_mul_f32_e32 v94, v85, v85
	v_mul_f32_e32 v95, v87, v87
	v_fmac_f32_e32 v94, v84, v84
	v_fmac_f32_e32 v95, v86, v86
	v_add_f32_e32 v100, v100, v101
	v_mul_f32_e32 v101, v89, v89
	v_add_f32_e32 v94, v94, v95
	v_mul_f32_e32 v95, v81, v81
	v_fmac_f32_e32 v101, v88, v88
	v_fmac_f32_e32 v95, v80, v80
	v_add_f32_e32 v100, v100, v101
	v_mul_f32_e32 v101, v91, v91
	v_add_f32_e32 v94, v94, v95
	v_mul_f32_e32 v95, v83, v83
	v_fmac_f32_e32 v101, v90, v90
	v_fmac_f32_e32 v95, v82, v82
	v_add_f32_e32 v100, v101, v100
	v_add_f32_e32 v94, v95, v94
	v_add_f32_e32 v100, v100, v94
	ds_bpermute_b32 v101, v158, v100
	v_cvt_pk_bf16_f32 v94, v88, v89
	v_cvt_pk_bf16_f32 v88, v84, v85
	v_or_b32_e32 v96, 32, v150
	v_ashrrev_i32_e32 v97, 31, v96
	s_waitcnt lgkmcnt(0)
	v_add_f32_e32 v84, v100, v101
	ds_bpermute_b32 v85, v157, v84
	v_lshlrev_b64 v[98:99], 11, v[96:97]
	v_lshl_add_u64 v[98:99], s[82:83], 0, v[98:99]
	v_lshl_add_u64 v[98:99], v[148:149], 1, v[98:99]
	v_cvt_pk_bf16_f32 v95, v90, v91
	v_cvt_pk_bf16_f32 v89, v86, v87
	v_cvt_pk_bf16_f32 v90, v80, v81
	v_cvt_pk_bf16_f32 v91, v82, v83
	global_store_dwordx4 v[98:99], v[92:95], off nt
	global_store_dwordx4 v[98:99], v[88:91], off offset:256 nt
	s_and_saveexec_b64 s[26:27], s[8:9]
	s_cbranch_execz .LBB0_948
	v_lshlrev_b64 v[80:81], 6, v[96:97]
	v_lshl_add_u64 v[80:81], s[16:17], 0, v[80:81]
	v_lshl_add_u64 v[80:81], s[24:25], 2, v[80:81]
	s_lshl_b32 s12, s36, 2
	s_waitcnt lgkmcnt(0)
	v_add_f32_e32 v82, v84, v85
	v_lshl_add_u64 v[80:81], v[80:81], 0, s[12:13]
	global_store_dword v[80:81], v82, off
.LBB0_948:
	s_or_b64 exec, exec, s[26:27]
	v_mul_f32_e32 v84, v77, v77
	s_waitcnt lgkmcnt(0)
	v_mul_f32_e32 v85, v79, v79
	v_fmac_f32_e32 v84, v76, v76
	v_fmac_f32_e32 v85, v78, v78
	v_cvt_pk_bf16_f32 v76, v76, v77
	v_cvt_pk_bf16_f32 v77, v78, v79
	v_mul_f32_e32 v78, v69, v69
	v_mul_f32_e32 v79, v71, v71
	v_fmac_f32_e32 v78, v68, v68
	v_fmac_f32_e32 v79, v70, v70
	v_add_f32_e32 v84, v84, v85
	v_mul_f32_e32 v85, v73, v73
	v_add_f32_e32 v78, v78, v79
	v_mul_f32_e32 v79, v65, v65
	v_fmac_f32_e32 v85, v72, v72
	v_fmac_f32_e32 v79, v64, v64
	v_add_f32_e32 v84, v84, v85
	v_mul_f32_e32 v85, v75, v75
	v_add_f32_e32 v78, v78, v79
	v_mul_f32_e32 v79, v67, v67
	v_fmac_f32_e32 v85, v74, v74
	v_fmac_f32_e32 v79, v66, v66
	v_add_f32_e32 v84, v85, v84
	v_add_f32_e32 v78, v79, v78
	v_add_f32_e32 v84, v84, v78
	ds_bpermute_b32 v85, v158, v84
	v_cvt_pk_bf16_f32 v78, v72, v73
	v_cvt_pk_bf16_f32 v72, v68, v69
	v_or_b32_e32 v80, 48, v150
	v_ashrrev_i32_e32 v81, 31, v80
	s_waitcnt lgkmcnt(0)
	v_add_f32_e32 v68, v84, v85
	ds_bpermute_b32 v69, v157, v68
	v_lshlrev_b64 v[82:83], 11, v[80:81]
	v_lshl_add_u64 v[82:83], s[82:83], 0, v[82:83]
	v_lshl_add_u64 v[82:83], v[148:149], 1, v[82:83]
	v_cvt_pk_bf16_f32 v79, v74, v75
	v_cvt_pk_bf16_f32 v73, v70, v71
	v_cvt_pk_bf16_f32 v74, v64, v65
	v_cvt_pk_bf16_f32 v75, v66, v67
	global_store_dwordx4 v[82:83], v[76:79], off nt
	global_store_dwordx4 v[82:83], v[72:75], off offset:256 nt
	s_and_saveexec_b64 s[26:27], s[8:9]
	s_cbranch_execz .LBB0_950
	v_lshlrev_b64 v[64:65], 6, v[80:81]
	v_lshl_add_u64 v[64:65], s[16:17], 0, v[64:65]
	v_lshl_add_u64 v[64:65], s[24:25], 2, v[64:65]
	s_lshl_b32 s12, s36, 2
	s_waitcnt lgkmcnt(0)
	v_add_f32_e32 v66, v68, v69
	v_lshl_add_u64 v[64:65], v[64:65], 0, s[12:13]
	global_store_dword v[64:65], v66, off
.LBB0_950:
	s_or_b64 exec, exec, s[26:27]
	v_mul_f32_e32 v68, v61, v61
	s_waitcnt lgkmcnt(0)
	v_mul_f32_e32 v69, v63, v63
	v_fmac_f32_e32 v68, v60, v60
	v_fmac_f32_e32 v69, v62, v62
	v_cvt_pk_bf16_f32 v60, v60, v61
	v_cvt_pk_bf16_f32 v61, v62, v63
	v_mul_f32_e32 v62, v53, v53
	v_mul_f32_e32 v63, v55, v55
	v_fmac_f32_e32 v62, v52, v52
	v_fmac_f32_e32 v63, v54, v54
	v_add_f32_e32 v68, v68, v69
	v_mul_f32_e32 v69, v57, v57
	v_add_f32_e32 v62, v62, v63
	v_mul_f32_e32 v63, v49, v49
	v_fmac_f32_e32 v69, v56, v56
	v_fmac_f32_e32 v63, v48, v48
	v_add_f32_e32 v68, v68, v69
	v_mul_f32_e32 v69, v59, v59
	v_add_f32_e32 v62, v62, v63
	v_mul_f32_e32 v63, v51, v51
	v_fmac_f32_e32 v69, v58, v58
	v_fmac_f32_e32 v63, v50, v50
	v_add_f32_e32 v68, v69, v68
	v_add_f32_e32 v62, v63, v62
	v_add_f32_e32 v68, v68, v62
	ds_bpermute_b32 v69, v158, v68
	v_cvt_pk_bf16_f32 v62, v56, v57
	v_cvt_pk_bf16_f32 v56, v52, v53
	v_add_u32_e32 v64, 0x80, v150
	v_ashrrev_i32_e32 v65, 31, v64
	s_waitcnt lgkmcnt(0)
	v_add_f32_e32 v52, v68, v69
	ds_bpermute_b32 v53, v157, v52
	v_lshlrev_b64 v[66:67], 11, v[64:65]
	v_lshl_add_u64 v[66:67], s[82:83], 0, v[66:67]
	v_lshl_add_u64 v[66:67], v[148:149], 1, v[66:67]
	v_cvt_pk_bf16_f32 v63, v58, v59
	v_cvt_pk_bf16_f32 v57, v54, v55
	v_cvt_pk_bf16_f32 v58, v48, v49
	v_cvt_pk_bf16_f32 v59, v50, v51
	global_store_dwordx4 v[66:67], v[60:63], off nt
	global_store_dwordx4 v[66:67], v[56:59], off offset:256 nt
	s_and_saveexec_b64 s[26:27], s[8:9]
	s_cbranch_execz .LBB0_952
	v_lshlrev_b64 v[48:49], 6, v[64:65]
	v_lshl_add_u64 v[48:49], s[16:17], 0, v[48:49]
	v_lshl_add_u64 v[48:49], s[24:25], 2, v[48:49]
	s_lshl_b32 s12, s36, 2
	s_waitcnt lgkmcnt(0)
	v_add_f32_e32 v50, v52, v53
	v_lshl_add_u64 v[48:49], v[48:49], 0, s[12:13]
	global_store_dword v[48:49], v50, off
.LBB0_952:
	s_or_b64 exec, exec, s[26:27]
	v_mul_f32_e32 v52, v45, v45
	s_waitcnt lgkmcnt(0)
	v_mul_f32_e32 v53, v47, v47
	v_fmac_f32_e32 v52, v44, v44
	v_fmac_f32_e32 v53, v46, v46
	v_cvt_pk_bf16_f32 v44, v44, v45
	v_cvt_pk_bf16_f32 v45, v46, v47
	v_mul_f32_e32 v46, v37, v37
	v_mul_f32_e32 v47, v39, v39
	v_fmac_f32_e32 v46, v36, v36
	v_fmac_f32_e32 v47, v38, v38
	v_add_f32_e32 v52, v52, v53
	v_mul_f32_e32 v53, v41, v41
	v_add_f32_e32 v46, v46, v47
	v_mul_f32_e32 v47, v33, v33
	v_fmac_f32_e32 v53, v40, v40
	v_fmac_f32_e32 v47, v32, v32
	v_add_f32_e32 v52, v52, v53
	v_mul_f32_e32 v53, v43, v43
	v_add_f32_e32 v46, v46, v47
	v_mul_f32_e32 v47, v35, v35
	v_fmac_f32_e32 v53, v42, v42
	v_fmac_f32_e32 v47, v34, v34
	v_add_f32_e32 v52, v53, v52
	v_add_f32_e32 v46, v47, v46
	v_add_f32_e32 v52, v52, v46
	ds_bpermute_b32 v53, v158, v52
	v_cvt_pk_bf16_f32 v46, v40, v41
	v_cvt_pk_bf16_f32 v40, v36, v37
	v_add_u32_e32 v48, 0x90, v150
	v_ashrrev_i32_e32 v49, 31, v48
	s_waitcnt lgkmcnt(0)
	v_add_f32_e32 v36, v52, v53
	ds_bpermute_b32 v37, v157, v36
	v_lshlrev_b64 v[50:51], 11, v[48:49]
	v_lshl_add_u64 v[50:51], s[82:83], 0, v[50:51]
	v_lshl_add_u64 v[50:51], v[148:149], 1, v[50:51]
	v_cvt_pk_bf16_f32 v47, v42, v43
	v_cvt_pk_bf16_f32 v41, v38, v39
	v_cvt_pk_bf16_f32 v42, v32, v33
	v_cvt_pk_bf16_f32 v43, v34, v35
	global_store_dwordx4 v[50:51], v[44:47], off nt
	global_store_dwordx4 v[50:51], v[40:43], off offset:256 nt
	s_and_saveexec_b64 s[26:27], s[8:9]
	s_cbranch_execz .LBB0_954
	v_lshlrev_b64 v[32:33], 6, v[48:49]
	v_lshl_add_u64 v[32:33], s[16:17], 0, v[32:33]
	v_lshl_add_u64 v[32:33], s[24:25], 2, v[32:33]
	s_lshl_b32 s12, s36, 2
	s_waitcnt lgkmcnt(0)
	v_add_f32_e32 v34, v36, v37
	v_lshl_add_u64 v[32:33], v[32:33], 0, s[12:13]
	global_store_dword v[32:33], v34, off
.LBB0_954:
	s_or_b64 exec, exec, s[26:27]
	v_mul_f32_e32 v36, v29, v29
	s_waitcnt lgkmcnt(0)
	v_mul_f32_e32 v37, v31, v31
	v_fmac_f32_e32 v36, v28, v28
	v_fmac_f32_e32 v37, v30, v30
	v_cvt_pk_bf16_f32 v28, v28, v29
	v_cvt_pk_bf16_f32 v29, v30, v31
	v_mul_f32_e32 v30, v21, v21
	v_mul_f32_e32 v31, v23, v23
	v_fmac_f32_e32 v30, v20, v20
	v_fmac_f32_e32 v31, v22, v22
	v_add_f32_e32 v36, v36, v37
	v_mul_f32_e32 v37, v25, v25
	v_add_f32_e32 v30, v30, v31
	v_mul_f32_e32 v31, v17, v17
	v_fmac_f32_e32 v37, v24, v24
	v_fmac_f32_e32 v31, v16, v16
	v_add_f32_e32 v36, v36, v37
	v_mul_f32_e32 v37, v27, v27
	v_add_f32_e32 v30, v30, v31
	v_mul_f32_e32 v31, v19, v19
	v_fmac_f32_e32 v37, v26, v26
	v_fmac_f32_e32 v31, v18, v18
	v_add_f32_e32 v36, v37, v36
	v_add_f32_e32 v30, v31, v30
	v_add_f32_e32 v36, v36, v30
	ds_bpermute_b32 v37, v158, v36
	v_cvt_pk_bf16_f32 v30, v24, v25
	v_cvt_pk_bf16_f32 v24, v20, v21
	v_add_u32_e32 v32, 0xa0, v150
	v_ashrrev_i32_e32 v33, 31, v32
	s_waitcnt lgkmcnt(0)
	v_add_f32_e32 v20, v36, v37
	ds_bpermute_b32 v21, v157, v20
	v_lshlrev_b64 v[34:35], 11, v[32:33]
	v_lshl_add_u64 v[34:35], s[82:83], 0, v[34:35]
	v_lshl_add_u64 v[34:35], v[148:149], 1, v[34:35]
	v_cvt_pk_bf16_f32 v31, v26, v27
	v_cvt_pk_bf16_f32 v25, v22, v23
	v_cvt_pk_bf16_f32 v26, v16, v17
	v_cvt_pk_bf16_f32 v27, v18, v19
	global_store_dwordx4 v[34:35], v[28:31], off nt
	global_store_dwordx4 v[34:35], v[24:27], off offset:256 nt
	s_and_saveexec_b64 s[26:27], s[8:9]
	s_cbranch_execz .LBB0_956
	v_lshlrev_b64 v[16:17], 6, v[32:33]
	v_lshl_add_u64 v[16:17], s[16:17], 0, v[16:17]
	v_lshl_add_u64 v[16:17], s[24:25], 2, v[16:17]
	s_lshl_b32 s12, s36, 2
	s_waitcnt lgkmcnt(0)
	v_add_f32_e32 v18, v20, v21
	v_lshl_add_u64 v[16:17], v[16:17], 0, s[12:13]
	global_store_dword v[16:17], v18, off
.LBB0_956:
	s_or_b64 exec, exec, s[26:27]
	v_mul_f32_e32 v20, v13, v13
	s_waitcnt lgkmcnt(0)
	v_mul_f32_e32 v21, v15, v15
	v_fmac_f32_e32 v20, v12, v12
	v_fmac_f32_e32 v21, v14, v14
	v_cvt_pk_bf16_f32 v12, v12, v13
	v_cvt_pk_bf16_f32 v13, v14, v15
	v_mul_f32_e32 v14, v5, v5
	v_mul_f32_e32 v15, v7, v7
	v_fmac_f32_e32 v14, v4, v4
	v_fmac_f32_e32 v15, v6, v6
	v_add_f32_e32 v20, v20, v21
	v_mul_f32_e32 v21, v9, v9
	v_add_f32_e32 v14, v14, v15
	v_mul_f32_e32 v15, v1, v1
	v_fmac_f32_e32 v21, v8, v8
	v_fmac_f32_e32 v15, v0, v0
	v_add_f32_e32 v20, v20, v21
	v_mul_f32_e32 v21, v11, v11
	v_add_f32_e32 v14, v14, v15
	v_mul_f32_e32 v15, v3, v3
	v_fmac_f32_e32 v21, v10, v10
	v_fmac_f32_e32 v15, v2, v2
	v_add_f32_e32 v20, v21, v20
	v_add_f32_e32 v14, v15, v14
	v_add_f32_e32 v20, v20, v14
	ds_bpermute_b32 v21, v158, v20
	v_cvt_pk_bf16_f32 v14, v8, v9
	v_cvt_pk_bf16_f32 v8, v4, v5
	v_add_u32_e32 v16, 0xb0, v150
	v_ashrrev_i32_e32 v17, 31, v16
	s_waitcnt lgkmcnt(0)
	v_add_f32_e32 v4, v20, v21
	ds_bpermute_b32 v5, v157, v4
	v_lshlrev_b64 v[18:19], 11, v[16:17]
	v_lshl_add_u64 v[18:19], s[82:83], 0, v[18:19]
	v_lshl_add_u64 v[18:19], v[148:149], 1, v[18:19]
	v_cvt_pk_bf16_f32 v15, v10, v11
	v_cvt_pk_bf16_f32 v9, v6, v7
	v_cvt_pk_bf16_f32 v10, v0, v1
	v_cvt_pk_bf16_f32 v11, v2, v3
	global_store_dwordx4 v[18:19], v[12:15], off nt
	global_store_dwordx4 v[18:19], v[8:11], off offset:256 nt
	s_and_saveexec_b64 s[26:27], s[8:9]
	s_cbranch_execz .LBB0_958
	v_lshlrev_b64 v[0:1], 6, v[16:17]
	v_lshl_add_u64 v[0:1], s[16:17], 0, v[0:1]
	v_lshl_add_u64 v[0:1], s[24:25], 2, v[0:1]
	s_lshl_b32 s12, s36, 2
	s_waitcnt lgkmcnt(0)
	v_add_f32_e32 v2, v4, v5
	v_lshl_add_u64 v[0:1], v[0:1], 0, s[12:13]
	global_store_dword v[0:1], v2, off
